# MLA tile loop: one static s_setprio 1 for waves 4-7, per-segment flips removed
# speedup vs baseline: 1.0086x; 1.0086x over previous
; DI int tid_pinned() { int t = threadIdx.x; asm volatile("" : "+v"(t)); return t; }
; DI u32 pk2(float a, float b) { f2_t v = {a, b}; bf2_t r = __builtin_convertvector(v, bf2_t); return __builtin_bit_cast(u32, r); }
; DI float bflo(u32 u) { return __uint_as_float(u << 16); }
; template <bool DIFF>
; DI void attn_phase(const AttnArgs& a, char* lds) {
;     ...
;     const int te_ = tid_pinned() & 63;
;     const int g = te_ >> 5, lane = te_;
;     const int qrow = qb * QROWS + rg * 32 + (te_ & 31);
;     const float lt = xor32_sum(l_sum);
;     const float inv = __builtin_amdgcn_rcpf(lt);
;     if (!DIFF) {
;       u32 go2 = (u32)qrow * (u32)a.ldg + (u32)(a.goff + h * 128 + 8 * g); pinu(go2);
;       u32 oo2 = (u32)qrow * 2048u + (u32)(h * 128 + 8 * g); pinu(oo2);
; #pragma unroll
;       for (int m = 0; m < NM; ++m)
; #pragma unroll
;         for (int bp = 0; bp < 2; ++bp) {
;           u32x2 pk[2];
;           const u32x4 gl = *(const u32x4*)(a.gate + go2 + 32 * m + 16 * bp);
;           const auto q0 = __builtin_amdgcn_permlane32_swap(gl[0], gl[2], false, false);
;           const auto q1 = __builtin_amdgcn_permlane32_swap(gl[1], gl[3], false, false);
;           u32x2 gsel[2]; gsel[0][0] = q0[0]; gsel[0][1] = q1[0]; gsel[1][0] = q0[1]; gsel[1][1] = q1[1];
; #pragma unroll
;           for (int bb = 0; bb < 2; ++bb) {
;             const int b = 2 * bp + bb;
;             const u32x2 gu = gsel[bb];
;             const float g0 = bflo(gu[0]), g1 = bfhi(gu[0]), g2 = bflo(gu[1]), g3 = bfhi(gu[1]);
;             const float y0 = o[m][4 * b] * inv * g0 * __builtin_amdgcn_rcpf(1.f + __expf(-g0));
;             const float y1 = o[m][4 * b + 1] * inv * g1 * __builtin_amdgcn_rcpf(1.f + __expf(-g1));
;             const float y2 = o[m][4 * b + 2] * inv * g2 * __builtin_amdgcn_rcpf(1.f + __expf(-g2));
;             const float y3 = o[m][4 * b + 3] * inv * g3 * __builtin_amdgcn_rcpf(1.f + __expf(-g3));
;             pk[bb][0] = pk2(y0, y1); pk[bb][1] = pk2(y2, y3);
;           }
;           const auto r0 = __builtin_amdgcn_permlane32_swap(pk[0][0], pk[1][0], false, false);
;           const auto r1 = __builtin_amdgcn_permlane32_swap(pk[0][1], pk[1][1], false, false);
;           u32x4 w; w[0] = r0[0]; w[1] = r1[0]; w[2] = r0[1]; w[3] = r1[1];
;           *(u32x4*)(a.og + oo2 + 32 * m + 16 * bp) = w;
;           __builtin_amdgcn_sched_barrier(0);
;         }
.LBB0_370:
	s_setprio 0
	v_mov_b32_e32 v0, v208
	s_lshl_b32 s0, s62, 7
	v_and_or_b32 v2, v0, 31, s6
	v_lshrrev_b32_e32 v0, 2, v0
	v_mul_lo_u32 v3, v2, s83
	v_and_or_b32 v4, v0, 8, s0
	v_add3_u32 v0, v4, v3, s84
	v_lshl_add_u32 v10, v2, 11, v4
	v_lshl_add_u64 v[2:3], v[0:1], 1, s[42:43]
	global_load_dwordx4 v[4:7], v[2:3], off
	v_mov_b32_e32 v0, v217
	s_nop 1
	v_permlane32_swap_b32_e32 v217, v0
	v_add_f32_e32 v0, v217, v0
	v_rcp_f32_e32 v0, v0
	v_mov_b32_e32 v11, v1
	s_add_i32 s33, s33, s34
	v_pk_mul_f32 v[12:13], v[66:67], v[0:1] op_sel_hi:[1,0]
	v_pk_mul_f32 v[14:15], v[68:69], v[0:1] op_sel_hi:[1,0]
	v_pk_mul_f32 v[8:9], v[64:65], v[0:1] op_sel_hi:[1,0]
	v_pk_mul_f32 v[64:65], v[70:71], v[0:1] op_sel_hi:[1,0]
	s_waitcnt vmcnt(0)
	v_mov_b32_e32 v67, v6
	v_mov_b32_e32 v69, v7
	s_nop 0
	v_permlane32_swap_b32_e32 v4, v67
	v_permlane32_swap_b32_e32 v5, v69
	v_lshlrev_b32_e32 v6, 16, v4
	v_and_b32_e32 v7, 0xffff0000, v4
	v_lshlrev_b32_e32 v4, 16, v5
	v_and_b32_e32 v5, 0xffff0000, v5
	v_lshlrev_b32_e32 v66, 16, v67
	v_and_b32_e32 v67, 0xffff0000, v67
	v_lshlrev_b32_e32 v68, 16, v69
	v_and_b32_e32 v69, 0xffff0000, v69
	v_mul_f32_e32 v70, 0xbfb8aa3b, v6
	v_pk_mul_f32 v[8:9], v[8:9], v[6:7]
	v_mul_f32_e32 v71, 0xbfb8aa3b, v7
	v_mul_f32_e32 v80, 0xbfb8aa3b, v4
	v_pk_mul_f32 v[6:7], v[12:13], v[4:5]
	v_mul_f32_e32 v81, 0xbfb8aa3b, v5
	v_mul_f32_e32 v82, 0xbfb8aa3b, v66
	v_pk_mul_f32 v[4:5], v[14:15], v[66:67]
	v_mul_f32_e32 v14, 0xbfb8aa3b, v67
	v_mul_f32_e32 v15, 0xbfb8aa3b, v68
	v_pk_mul_f32 v[12:13], v[64:65], v[68:69]
	v_mul_f32_e32 v64, 0xbfb8aa3b, v69
	v_exp_f32_e32 v65, v70
	v_exp_f32_e32 v66, v71
	v_exp_f32_e32 v67, v80
	v_exp_f32_e32 v68, v81
	v_exp_f32_e32 v69, v82
	v_exp_f32_e32 v14, v14
	v_exp_f32_e32 v15, v15
	v_exp_f32_e32 v64, v64
	v_add_f32_e32 v65, 1.0, v65
	v_add_f32_e32 v66, 1.0, v66
	v_add_f32_e32 v67, 1.0, v67
	v_add_f32_e32 v68, 1.0, v68
	v_add_f32_e32 v69, 1.0, v69
	v_add_f32_e32 v70, 1.0, v14
	v_add_f32_e32 v71, 1.0, v15
	v_add_f32_e32 v80, 1.0, v64
	v_rcp_f32_e32 v14, v65
	v_rcp_f32_e32 v15, v66
	v_rcp_f32_e32 v64, v67
	v_rcp_f32_e32 v65, v68
	v_rcp_f32_e32 v66, v69
	v_rcp_f32_e32 v67, v70
	v_rcp_f32_e32 v68, v71
	v_rcp_f32_e32 v69, v80
	v_pk_mul_f32 v[8:9], v[8:9], v[14:15]
	v_pk_mul_f32 v[14:15], v[6:7], v[64:65]
	v_pk_mul_f32 v[4:5], v[4:5], v[66:67]
	v_pk_mul_f32 v[12:13], v[12:13], v[68:69]
	v_cvt_pk_bf16_f32 v6, v8, v9
	v_cvt_pk_bf16_f32 v7, v14, v15
	v_cvt_pk_bf16_f32 v8, v4, v5
	v_cvt_pk_bf16_f32 v9, v12, v13
	s_nop 0
	v_permlane32_swap_b32_e32 v6, v8
	v_permlane32_swap_b32_e32 v7, v9
	v_lshl_add_u64 v[4:5], v[10:11], 1, s[24:25]
	global_store_dwordx4 v[4:5], v[6:9], off
	global_load_dwordx4 v[6:9], v[2:3], off offset:32
	v_pk_mul_f32 v[10:11], v[72:73], v[0:1] op_sel_hi:[1,0]
	v_pk_mul_f32 v[12:13], v[74:75], v[0:1] op_sel_hi:[1,0]
	v_pk_mul_f32 v[14:15], v[76:77], v[0:1] op_sel_hi:[1,0]
	v_pk_mul_f32 v[64:65], v[78:79], v[0:1] op_sel_hi:[1,0]
	s_waitcnt vmcnt(0)
	v_mov_b32_e32 v67, v8
	v_mov_b32_e32 v69, v9
	s_nop 0
	v_permlane32_swap_b32_e32 v6, v67
	v_permlane32_swap_b32_e32 v7, v69
	v_lshlrev_b32_e32 v8, 16, v6
	v_and_b32_e32 v9, 0xffff0000, v6
	v_lshlrev_b32_e32 v6, 16, v7
	v_and_b32_e32 v7, 0xffff0000, v7
	v_lshlrev_b32_e32 v66, 16, v67
	v_and_b32_e32 v67, 0xffff0000, v67
	v_lshlrev_b32_e32 v68, 16, v69
	v_and_b32_e32 v69, 0xffff0000, v69
	v_mul_f32_e32 v70, 0xbfb8aa3b, v8
	v_pk_mul_f32 v[10:11], v[10:11], v[8:9]
	v_mul_f32_e32 v71, 0xbfb8aa3b, v9
	v_mul_f32_e32 v72, 0xbfb8aa3b, v6
	v_pk_mul_f32 v[8:9], v[12:13], v[6:7]
	v_mul_f32_e32 v73, 0xbfb8aa3b, v7
	v_mul_f32_e32 v74, 0xbfb8aa3b, v66
	v_pk_mul_f32 v[6:7], v[14:15], v[66:67]
	v_mul_f32_e32 v14, 0xbfb8aa3b, v67
	v_mul_f32_e32 v15, 0xbfb8aa3b, v68
	v_pk_mul_f32 v[12:13], v[64:65], v[68:69]
	v_mul_f32_e32 v64, 0xbfb8aa3b, v69
	v_exp_f32_e32 v65, v70
	v_exp_f32_e32 v66, v71
	v_exp_f32_e32 v67, v72
	v_exp_f32_e32 v68, v73
	v_exp_f32_e32 v69, v74
	v_exp_f32_e32 v14, v14
	v_exp_f32_e32 v15, v15
	v_exp_f32_e32 v64, v64
	v_add_f32_e32 v65, 1.0, v65
	v_add_f32_e32 v66, 1.0, v66
	v_add_f32_e32 v67, 1.0, v67
	v_add_f32_e32 v68, 1.0, v68
	v_add_f32_e32 v69, 1.0, v69
	v_add_f32_e32 v70, 1.0, v14
	v_add_f32_e32 v71, 1.0, v15
	v_add_f32_e32 v72, 1.0, v64
	v_rcp_f32_e32 v14, v65
	v_rcp_f32_e32 v15, v66
	v_rcp_f32_e32 v64, v67
	v_rcp_f32_e32 v65, v68
	v_rcp_f32_e32 v66, v69
	v_rcp_f32_e32 v67, v70
	v_rcp_f32_e32 v68, v71
	v_rcp_f32_e32 v69, v72
	v_pk_mul_f32 v[10:11], v[10:11], v[14:15]
	v_pk_mul_f32 v[8:9], v[8:9], v[64:65]
	v_pk_mul_f32 v[14:15], v[6:7], v[66:67]
	v_pk_mul_f32 v[12:13], v[12:13], v[68:69]
	v_cvt_pk_bf16_f32 v6, v10, v11
	v_cvt_pk_bf16_f32 v7, v8, v9
	v_cvt_pk_bf16_f32 v8, v14, v15
	v_cvt_pk_bf16_f32 v9, v12, v13
	s_nop 0
	v_permlane32_swap_b32_e32 v6, v8
	v_permlane32_swap_b32_e32 v7, v9
	global_store_dwordx4 v[4:5], v[6:9], off offset:32
	global_load_dwordx4 v[6:9], v[2:3], off offset:64
	v_pk_mul_f32 v[12:13], v[50:51], v[0:1] op_sel_hi:[1,0]
	v_pk_mul_f32 v[14:15], v[52:53], v[0:1] op_sel_hi:[1,0]
	v_pk_mul_f32 v[10:11], v[48:49], v[0:1] op_sel_hi:[1,0]
	v_pk_mul_f32 v[48:49], v[54:55], v[0:1] op_sel_hi:[1,0]
	s_waitcnt vmcnt(0)
; DI u32 pk2(float a, float b) { f2_t v = {a, b}; bf2_t r = __builtin_convertvector(v, bf2_t); return __builtin_bit_cast(u32, r); }
; DI float bflo(u32 u) { return __uint_as_float(u << 16); }
; DI float bfhi(u32 u) { return __uint_as_float(u & 0xffff0000u); }
; template <bool DIFF>
; DI void attn_phase(const AttnArgs& a, char* lds) {
;     ...
; #pragma unroll
;       for (int m = 0; m < NM; ++m)
; #pragma unroll
;         for (int bp = 0; bp < 2; ++bp) {
;           u32x2 pk[2];
;           const u32x4 gl = *(const u32x4*)(a.gate + go2 + 32 * m + 16 * bp);
;           const auto q0 = __builtin_amdgcn_permlane32_swap(gl[0], gl[2], false, false);
;           const auto q1 = __builtin_amdgcn_permlane32_swap(gl[1], gl[3], false, false);
;           u32x2 gsel[2]; gsel[0][0] = q0[0]; gsel[0][1] = q1[0]; gsel[1][0] = q0[1]; gsel[1][1] = q1[1];
; #pragma unroll
;           for (int bb = 0; bb < 2; ++bb) {
;             const int b = 2 * bp + bb;
;             const u32x2 gu = gsel[bb];
;             const float g0 = bflo(gu[0]), g1 = bfhi(gu[0]), g2 = bflo(gu[1]), g3 = bfhi(gu[1]);
;             const float y0 = o[m][4 * b] * inv * g0 * __builtin_amdgcn_rcpf(1.f + __expf(-g0));
;             const float y1 = o[m][4 * b + 1] * inv * g1 * __builtin_amdgcn_rcpf(1.f + __expf(-g1));
;             const float y2 = o[m][4 * b + 2] * inv * g2 * __builtin_amdgcn_rcpf(1.f + __expf(-g2));
;             const float y3 = o[m][4 * b + 3] * inv * g3 * __builtin_amdgcn_rcpf(1.f + __expf(-g3));
;             pk[bb][0] = pk2(y0, y1); pk[bb][1] = pk2(y2, y3);
;           }
;           const auto r0 = __builtin_amdgcn_permlane32_swap(pk[0][0], pk[1][0], false, false);
;           const auto r1 = __builtin_amdgcn_permlane32_swap(pk[0][1], pk[1][1], false, false);
;           u32x4 w; w[0] = r0[0]; w[1] = r1[0]; w[2] = r0[1]; w[3] = r1[1];
;           *(u32x4*)(a.og + oo2 + 32 * m + 16 * bp) = w;
;           __builtin_amdgcn_sched_barrier(0);
;         }
	v_mov_b32_e32 v51, v8
	v_mov_b32_e32 v53, v9
	s_nop 0
	v_permlane32_swap_b32_e32 v6, v51
	v_permlane32_swap_b32_e32 v7, v53
	v_lshlrev_b32_e32 v8, 16, v6
	v_and_b32_e32 v9, 0xffff0000, v6
	v_lshlrev_b32_e32 v6, 16, v7
	v_and_b32_e32 v7, 0xffff0000, v7
	v_lshlrev_b32_e32 v50, 16, v51
	v_and_b32_e32 v51, 0xffff0000, v51
	v_lshlrev_b32_e32 v52, 16, v53
	v_and_b32_e32 v53, 0xffff0000, v53
	v_mul_f32_e32 v54, 0xbfb8aa3b, v8
	v_pk_mul_f32 v[10:11], v[10:11], v[8:9]
	v_mul_f32_e32 v55, 0xbfb8aa3b, v9
	v_mul_f32_e32 v64, 0xbfb8aa3b, v6
	v_pk_mul_f32 v[8:9], v[12:13], v[6:7]
	v_mul_f32_e32 v65, 0xbfb8aa3b, v7
	v_mul_f32_e32 v66, 0xbfb8aa3b, v50
	v_pk_mul_f32 v[6:7], v[14:15], v[50:51]
	v_mul_f32_e32 v14, 0xbfb8aa3b, v51
	v_mul_f32_e32 v15, 0xbfb8aa3b, v52
	v_pk_mul_f32 v[12:13], v[48:49], v[52:53]
	v_mul_f32_e32 v48, 0xbfb8aa3b, v53
	v_exp_f32_e32 v49, v54
	v_exp_f32_e32 v50, v55
	v_exp_f32_e32 v51, v64
	v_exp_f32_e32 v52, v65
	v_exp_f32_e32 v53, v66
	v_exp_f32_e32 v14, v14
	v_exp_f32_e32 v15, v15
	v_exp_f32_e32 v48, v48
	v_add_f32_e32 v49, 1.0, v49
	v_add_f32_e32 v50, 1.0, v50
	v_add_f32_e32 v51, 1.0, v51
	v_add_f32_e32 v52, 1.0, v52
	v_add_f32_e32 v53, 1.0, v53
	v_add_f32_e32 v54, 1.0, v14
	v_add_f32_e32 v55, 1.0, v15
	v_add_f32_e32 v64, 1.0, v48
	v_rcp_f32_e32 v14, v49
	v_rcp_f32_e32 v15, v50
	v_rcp_f32_e32 v48, v51
	v_rcp_f32_e32 v49, v52
	v_rcp_f32_e32 v50, v53
	v_rcp_f32_e32 v51, v54
	v_rcp_f32_e32 v52, v55
	v_rcp_f32_e32 v53, v64
	v_pk_mul_f32 v[10:11], v[10:11], v[14:15]
	v_pk_mul_f32 v[8:9], v[8:9], v[48:49]
	v_pk_mul_f32 v[14:15], v[6:7], v[50:51]
	v_pk_mul_f32 v[12:13], v[12:13], v[52:53]
	v_cvt_pk_bf16_f32 v6, v10, v11
	v_cvt_pk_bf16_f32 v7, v8, v9
	v_cvt_pk_bf16_f32 v8, v14, v15
	v_cvt_pk_bf16_f32 v9, v12, v13
	s_nop 0
	v_permlane32_swap_b32_e32 v6, v8
	v_permlane32_swap_b32_e32 v7, v9
	global_store_dwordx4 v[4:5], v[6:9], off offset:64
	global_load_dwordx4 v[6:9], v[2:3], off offset:96
	v_pk_mul_f32 v[10:11], v[56:57], v[0:1] op_sel_hi:[1,0]
	v_pk_mul_f32 v[12:13], v[58:59], v[0:1] op_sel_hi:[1,0]
	v_pk_mul_f32 v[14:15], v[60:61], v[0:1] op_sel_hi:[1,0]
	v_pk_mul_f32 v[48:49], v[62:63], v[0:1] op_sel_hi:[1,0]
	s_waitcnt vmcnt(0)
	v_mov_b32_e32 v51, v8
	v_mov_b32_e32 v53, v9
	s_nop 0
	v_permlane32_swap_b32_e32 v6, v51
	v_permlane32_swap_b32_e32 v7, v53
	v_lshlrev_b32_e32 v8, 16, v6
	v_and_b32_e32 v9, 0xffff0000, v6
	v_lshlrev_b32_e32 v6, 16, v7
	v_and_b32_e32 v7, 0xffff0000, v7
	v_lshlrev_b32_e32 v50, 16, v51
	v_and_b32_e32 v51, 0xffff0000, v51
	v_lshlrev_b32_e32 v52, 16, v53
	v_and_b32_e32 v53, 0xffff0000, v53
	v_mul_f32_e32 v54, 0xbfb8aa3b, v8
	v_pk_mul_f32 v[10:11], v[10:11], v[8:9]
	v_mul_f32_e32 v55, 0xbfb8aa3b, v9
	v_mul_f32_e32 v56, 0xbfb8aa3b, v6
	v_pk_mul_f32 v[8:9], v[12:13], v[6:7]
	v_mul_f32_e32 v57, 0xbfb8aa3b, v7
	v_mul_f32_e32 v58, 0xbfb8aa3b, v50
	v_pk_mul_f32 v[6:7], v[14:15], v[50:51]
	v_mul_f32_e32 v14, 0xbfb8aa3b, v51
	v_mul_f32_e32 v15, 0xbfb8aa3b, v52
	v_pk_mul_f32 v[12:13], v[48:49], v[52:53]
	v_mul_f32_e32 v48, 0xbfb8aa3b, v53
	v_exp_f32_e32 v49, v54
	v_exp_f32_e32 v50, v55
	v_exp_f32_e32 v51, v56
	v_exp_f32_e32 v52, v57
	v_exp_f32_e32 v53, v58
	v_exp_f32_e32 v14, v14
	v_exp_f32_e32 v15, v15
	v_exp_f32_e32 v48, v48
	v_add_f32_e32 v49, 1.0, v49
	v_add_f32_e32 v50, 1.0, v50
	v_add_f32_e32 v51, 1.0, v51
	v_add_f32_e32 v52, 1.0, v52
	v_add_f32_e32 v53, 1.0, v53
	v_add_f32_e32 v54, 1.0, v14
	v_add_f32_e32 v55, 1.0, v15
	v_add_f32_e32 v56, 1.0, v48
	v_rcp_f32_e32 v14, v49
	v_rcp_f32_e32 v15, v50
	v_rcp_f32_e32 v48, v51
	v_rcp_f32_e32 v49, v52
	v_rcp_f32_e32 v50, v53
	v_rcp_f32_e32 v51, v54
	v_rcp_f32_e32 v52, v55
	v_rcp_f32_e32 v53, v56
	v_pk_mul_f32 v[10:11], v[10:11], v[14:15]
	v_pk_mul_f32 v[8:9], v[8:9], v[48:49]
	v_pk_mul_f32 v[14:15], v[6:7], v[50:51]
	v_pk_mul_f32 v[12:13], v[12:13], v[52:53]
	v_cvt_pk_bf16_f32 v6, v10, v11
	v_cvt_pk_bf16_f32 v7, v8, v9
	v_cvt_pk_bf16_f32 v8, v14, v15
	v_cvt_pk_bf16_f32 v9, v12, v13
	s_nop 0
	v_permlane32_swap_b32_e32 v6, v8
	v_permlane32_swap_b32_e32 v7, v9
	global_store_dwordx4 v[4:5], v[6:9], off offset:96
	global_load_dwordx4 v[6:9], v[2:3], off offset:128
	v_pk_mul_f32 v[12:13], v[34:35], v[0:1] op_sel_hi:[1,0]
	v_pk_mul_f32 v[14:15], v[36:37], v[0:1] op_sel_hi:[1,0]
	v_pk_mul_f32 v[10:11], v[32:33], v[0:1] op_sel_hi:[1,0]
	v_pk_mul_f32 v[32:33], v[38:39], v[0:1] op_sel_hi:[1,0]
	s_waitcnt vmcnt(0)
	v_mov_b32_e32 v35, v8
	v_mov_b32_e32 v37, v9
	s_nop 0
	v_permlane32_swap_b32_e32 v6, v35
	v_permlane32_swap_b32_e32 v7, v37
	v_lshlrev_b32_e32 v8, 16, v6
	v_and_b32_e32 v9, 0xffff0000, v6
	v_lshlrev_b32_e32 v6, 16, v7
	v_and_b32_e32 v7, 0xffff0000, v7
	v_lshlrev_b32_e32 v34, 16, v35
	v_and_b32_e32 v35, 0xffff0000, v35
	v_lshlrev_b32_e32 v36, 16, v37
	v_and_b32_e32 v37, 0xffff0000, v37
	v_mul_f32_e32 v38, 0xbfb8aa3b, v8
	v_pk_mul_f32 v[10:11], v[10:11], v[8:9]
	v_mul_f32_e32 v39, 0xbfb8aa3b, v9
	v_mul_f32_e32 v48, 0xbfb8aa3b, v6
	v_pk_mul_f32 v[8:9], v[12:13], v[6:7]
	v_mul_f32_e32 v49, 0xbfb8aa3b, v7
	v_mul_f32_e32 v50, 0xbfb8aa3b, v34
	v_pk_mul_f32 v[6:7], v[14:15], v[34:35]
	v_mul_f32_e32 v14, 0xbfb8aa3b, v35
	v_mul_f32_e32 v15, 0xbfb8aa3b, v36
	v_pk_mul_f32 v[12:13], v[32:33], v[36:37]
	v_mul_f32_e32 v32, 0xbfb8aa3b, v37
	v_exp_f32_e32 v33, v38
	v_exp_f32_e32 v34, v39
	v_exp_f32_e32 v35, v48
	v_exp_f32_e32 v36, v49
	v_exp_f32_e32 v37, v50
	v_exp_f32_e32 v14, v14
	v_exp_f32_e32 v15, v15
	v_exp_f32_e32 v32, v32
	v_add_f32_e32 v33, 1.0, v33
	v_add_f32_e32 v34, 1.0, v34
	v_add_f32_e32 v35, 1.0, v35
	v_add_f32_e32 v36, 1.0, v36
	v_add_f32_e32 v37, 1.0, v37
	v_add_f32_e32 v38, 1.0, v14
	v_add_f32_e32 v39, 1.0, v15
	v_add_f32_e32 v48, 1.0, v32
	v_rcp_f32_e32 v14, v33
	v_rcp_f32_e32 v15, v34
	v_rcp_f32_e32 v32, v35
	v_rcp_f32_e32 v33, v36
	v_rcp_f32_e32 v34, v37
	v_rcp_f32_e32 v35, v38
	v_rcp_f32_e32 v36, v39
	v_rcp_f32_e32 v37, v48
	v_pk_mul_f32 v[10:11], v[10:11], v[14:15]
	v_pk_mul_f32 v[8:9], v[8:9], v[32:33]
	v_pk_mul_f32 v[14:15], v[6:7], v[34:35]
	v_pk_mul_f32 v[12:13], v[12:13], v[36:37]
	v_cvt_pk_bf16_f32 v6, v10, v11
	v_cvt_pk_bf16_f32 v7, v8, v9
	v_cvt_pk_bf16_f32 v8, v14, v15
	v_cvt_pk_bf16_f32 v9, v12, v13
	s_nop 0
	v_permlane32_swap_b32_e32 v6, v8
	v_permlane32_swap_b32_e32 v7, v9
	global_store_dwordx4 v[4:5], v[6:9], off offset:128
	global_load_dwordx4 v[6:9], v[2:3], off offset:160
	v_pk_mul_f32 v[10:11], v[40:41], v[0:1] op_sel_hi:[1,0]
	v_pk_mul_f32 v[12:13], v[42:43], v[0:1] op_sel_hi:[1,0]
	v_pk_mul_f32 v[14:15], v[44:45], v[0:1] op_sel_hi:[1,0]
	v_pk_mul_f32 v[32:33], v[46:47], v[0:1] op_sel_hi:[1,0]
	s_waitcnt vmcnt(0)
; DI u32 pk2(float a, float b) { f2_t v = {a, b}; bf2_t r = __builtin_convertvector(v, bf2_t); return __builtin_bit_cast(u32, r); }
; DI float bflo(u32 u) { return __uint_as_float(u << 16); }
; DI float bfhi(u32 u) { return __uint_as_float(u & 0xffff0000u); }
; template <bool DIFF>
; DI void attn_phase(const AttnArgs& a, char* lds) {
;     ...
; #pragma unroll
;       for (int m = 0; m < NM; ++m)
; #pragma unroll
;         for (int bp = 0; bp < 2; ++bp) {
;           u32x2 pk[2];
;           const u32x4 gl = *(const u32x4*)(a.gate + go2 + 32 * m + 16 * bp);
;           const auto q0 = __builtin_amdgcn_permlane32_swap(gl[0], gl[2], false, false);
;           const auto q1 = __builtin_amdgcn_permlane32_swap(gl[1], gl[3], false, false);
;           u32x2 gsel[2]; gsel[0][0] = q0[0]; gsel[0][1] = q1[0]; gsel[1][0] = q0[1]; gsel[1][1] = q1[1];
; #pragma unroll
;           for (int bb = 0; bb < 2; ++bb) {
;             const int b = 2 * bp + bb;
;             const u32x2 gu = gsel[bb];
;             const float g0 = bflo(gu[0]), g1 = bfhi(gu[0]), g2 = bflo(gu[1]), g3 = bfhi(gu[1]);
;             const float y0 = o[m][4 * b] * inv * g0 * __builtin_amdgcn_rcpf(1.f + __expf(-g0));
;             const float y1 = o[m][4 * b + 1] * inv * g1 * __builtin_amdgcn_rcpf(1.f + __expf(-g1));
;             const float y2 = o[m][4 * b + 2] * inv * g2 * __builtin_amdgcn_rcpf(1.f + __expf(-g2));
;             const float y3 = o[m][4 * b + 3] * inv * g3 * __builtin_amdgcn_rcpf(1.f + __expf(-g3));
;             pk[bb][0] = pk2(y0, y1); pk[bb][1] = pk2(y2, y3);
;           }
;           const auto r0 = __builtin_amdgcn_permlane32_swap(pk[0][0], pk[1][0], false, false);
;           const auto r1 = __builtin_amdgcn_permlane32_swap(pk[0][1], pk[1][1], false, false);
;           u32x4 w; w[0] = r0[0]; w[1] = r1[0]; w[2] = r0[1]; w[3] = r1[1];
;           *(u32x4*)(a.og + oo2 + 32 * m + 16 * bp) = w;
;           __builtin_amdgcn_sched_barrier(0);
;         }
	v_mov_b32_e32 v35, v8
	v_mov_b32_e32 v37, v9
	s_nop 0
	v_permlane32_swap_b32_e32 v6, v35
	v_permlane32_swap_b32_e32 v7, v37
	v_lshlrev_b32_e32 v8, 16, v6
	v_and_b32_e32 v9, 0xffff0000, v6
	v_lshlrev_b32_e32 v6, 16, v7
	v_and_b32_e32 v7, 0xffff0000, v7
	v_lshlrev_b32_e32 v34, 16, v35
	v_and_b32_e32 v35, 0xffff0000, v35
	v_lshlrev_b32_e32 v36, 16, v37
	v_and_b32_e32 v37, 0xffff0000, v37
	v_mul_f32_e32 v38, 0xbfb8aa3b, v8
	v_pk_mul_f32 v[10:11], v[10:11], v[8:9]
	v_mul_f32_e32 v39, 0xbfb8aa3b, v9
	v_mul_f32_e32 v40, 0xbfb8aa3b, v6
	v_pk_mul_f32 v[8:9], v[12:13], v[6:7]
	v_mul_f32_e32 v41, 0xbfb8aa3b, v7
	v_mul_f32_e32 v42, 0xbfb8aa3b, v34
	v_pk_mul_f32 v[6:7], v[14:15], v[34:35]
	v_mul_f32_e32 v14, 0xbfb8aa3b, v35
	v_mul_f32_e32 v15, 0xbfb8aa3b, v36
	v_pk_mul_f32 v[12:13], v[32:33], v[36:37]
	v_mul_f32_e32 v32, 0xbfb8aa3b, v37
	v_exp_f32_e32 v33, v38
	v_exp_f32_e32 v34, v39
	v_exp_f32_e32 v35, v40
	v_exp_f32_e32 v36, v41
	v_exp_f32_e32 v37, v42
	v_exp_f32_e32 v14, v14
	v_exp_f32_e32 v15, v15
	v_exp_f32_e32 v32, v32
	v_add_f32_e32 v33, 1.0, v33
	v_add_f32_e32 v34, 1.0, v34
	v_add_f32_e32 v35, 1.0, v35
	v_add_f32_e32 v36, 1.0, v36
	v_add_f32_e32 v37, 1.0, v37
	v_add_f32_e32 v38, 1.0, v14
	v_add_f32_e32 v39, 1.0, v15
	v_add_f32_e32 v40, 1.0, v32
	v_rcp_f32_e32 v14, v33
	v_rcp_f32_e32 v15, v34
	v_rcp_f32_e32 v32, v35
	v_rcp_f32_e32 v33, v36
	v_rcp_f32_e32 v34, v37
	v_rcp_f32_e32 v35, v38
	v_rcp_f32_e32 v36, v39
	v_rcp_f32_e32 v37, v40
	v_pk_mul_f32 v[10:11], v[10:11], v[14:15]
	v_pk_mul_f32 v[8:9], v[8:9], v[32:33]
	v_pk_mul_f32 v[14:15], v[6:7], v[34:35]
	v_pk_mul_f32 v[12:13], v[12:13], v[36:37]
	v_cvt_pk_bf16_f32 v6, v10, v11
	v_cvt_pk_bf16_f32 v7, v8, v9
	v_cvt_pk_bf16_f32 v8, v14, v15
	v_cvt_pk_bf16_f32 v9, v12, v13
	s_nop 0
	v_permlane32_swap_b32_e32 v6, v8
	v_permlane32_swap_b32_e32 v7, v9
	global_store_dwordx4 v[4:5], v[6:9], off offset:160
	global_load_dwordx4 v[6:9], v[2:3], off offset:192
	v_pk_mul_f32 v[12:13], v[18:19], v[0:1] op_sel_hi:[1,0]
	v_pk_mul_f32 v[14:15], v[20:21], v[0:1] op_sel_hi:[1,0]
	v_pk_mul_f32 v[10:11], v[16:17], v[0:1] op_sel_hi:[1,0]
	v_pk_mul_f32 v[16:17], v[22:23], v[0:1] op_sel_hi:[1,0]
	s_waitcnt vmcnt(0)
	v_mov_b32_e32 v19, v8
	v_mov_b32_e32 v21, v9
	s_nop 0
	v_permlane32_swap_b32_e32 v6, v19
	v_permlane32_swap_b32_e32 v7, v21
	v_lshlrev_b32_e32 v8, 16, v6
	v_and_b32_e32 v9, 0xffff0000, v6
	v_lshlrev_b32_e32 v6, 16, v7
	v_and_b32_e32 v7, 0xffff0000, v7
	v_lshlrev_b32_e32 v18, 16, v19
	v_and_b32_e32 v19, 0xffff0000, v19
	v_lshlrev_b32_e32 v20, 16, v21
	v_and_b32_e32 v21, 0xffff0000, v21
	v_mul_f32_e32 v22, 0xbfb8aa3b, v8
	v_pk_mul_f32 v[10:11], v[10:11], v[8:9]
	v_mul_f32_e32 v23, 0xbfb8aa3b, v9
	v_mul_f32_e32 v32, 0xbfb8aa3b, v6
	v_pk_mul_f32 v[8:9], v[12:13], v[6:7]
	v_mul_f32_e32 v33, 0xbfb8aa3b, v7
	v_mul_f32_e32 v34, 0xbfb8aa3b, v18
	v_pk_mul_f32 v[6:7], v[14:15], v[18:19]
	v_mul_f32_e32 v14, 0xbfb8aa3b, v19
	v_mul_f32_e32 v15, 0xbfb8aa3b, v20
	v_pk_mul_f32 v[12:13], v[16:17], v[20:21]
	v_mul_f32_e32 v16, 0xbfb8aa3b, v21
	v_exp_f32_e32 v17, v22
	v_exp_f32_e32 v18, v23
	v_exp_f32_e32 v19, v32
	v_exp_f32_e32 v20, v33
	v_exp_f32_e32 v21, v34
	v_exp_f32_e32 v14, v14
	v_exp_f32_e32 v15, v15
	v_exp_f32_e32 v16, v16
	v_add_f32_e32 v17, 1.0, v17
	v_add_f32_e32 v18, 1.0, v18
	v_add_f32_e32 v19, 1.0, v19
	v_add_f32_e32 v20, 1.0, v20
	v_add_f32_e32 v21, 1.0, v21
	v_add_f32_e32 v22, 1.0, v14
	v_add_f32_e32 v23, 1.0, v15
	v_add_f32_e32 v32, 1.0, v16
	v_rcp_f32_e32 v14, v17
	v_rcp_f32_e32 v15, v18
	v_rcp_f32_e32 v16, v19
	v_rcp_f32_e32 v17, v20
	v_rcp_f32_e32 v18, v21
	v_rcp_f32_e32 v19, v22
	v_rcp_f32_e32 v20, v23
	v_rcp_f32_e32 v21, v32
	v_pk_mul_f32 v[10:11], v[10:11], v[14:15]
	v_pk_mul_f32 v[8:9], v[8:9], v[16:17]
	v_pk_mul_f32 v[14:15], v[6:7], v[18:19]
	v_pk_mul_f32 v[12:13], v[12:13], v[20:21]
	v_cvt_pk_bf16_f32 v6, v10, v11
	v_cvt_pk_bf16_f32 v7, v8, v9
	v_cvt_pk_bf16_f32 v8, v14, v15
	v_cvt_pk_bf16_f32 v9, v12, v13
	s_nop 0
	v_permlane32_swap_b32_e32 v6, v8
	v_permlane32_swap_b32_e32 v7, v9
	global_store_dwordx4 v[4:5], v[6:9], off offset:192
	global_load_dwordx4 v[6:9], v[2:3], off offset:224
	v_pk_mul_f32 v[2:3], v[24:25], v[0:1] op_sel_hi:[1,0]
	v_pk_mul_f32 v[10:11], v[26:27], v[0:1] op_sel_hi:[1,0]
	v_pk_mul_f32 v[12:13], v[28:29], v[0:1] op_sel_hi:[1,0]
	v_pk_mul_f32 v[14:15], v[30:31], v[0:1] op_sel_hi:[1,0]
	s_waitcnt vmcnt(0)
	v_mov_b32_e32 v0, v8
	v_mov_b32_e32 v19, v9
	s_nop 0
	v_permlane32_swap_b32_e32 v6, v0
	v_permlane32_swap_b32_e32 v7, v19
	v_lshlrev_b32_e32 v8, 16, v6
	v_and_b32_e32 v9, 0xffff0000, v6
	v_lshlrev_b32_e32 v6, 16, v7
	v_and_b32_e32 v7, 0xffff0000, v7
	v_lshlrev_b32_e32 v16, 16, v0
	v_and_b32_e32 v17, 0xffff0000, v0
	v_lshlrev_b32_e32 v18, 16, v19
	v_and_b32_e32 v19, 0xffff0000, v19
	v_mul_f32_e32 v0, 0xbfb8aa3b, v8
	v_pk_mul_f32 v[2:3], v[2:3], v[8:9]
	v_mul_f32_e32 v20, 0xbfb8aa3b, v9
	v_mul_f32_e32 v21, 0xbfb8aa3b, v6
	v_pk_mul_f32 v[8:9], v[10:11], v[6:7]
	v_mul_f32_e32 v22, 0xbfb8aa3b, v7
	v_mul_f32_e32 v23, 0xbfb8aa3b, v16
	v_pk_mul_f32 v[6:7], v[12:13], v[16:17]
	v_mul_f32_e32 v12, 0xbfb8aa3b, v17
	v_mul_f32_e32 v13, 0xbfb8aa3b, v18
	v_pk_mul_f32 v[10:11], v[14:15], v[18:19]
	v_mul_f32_e32 v14, 0xbfb8aa3b, v19
	v_exp_f32_e32 v0, v0
	v_exp_f32_e32 v15, v20
	v_exp_f32_e32 v16, v21
	v_exp_f32_e32 v17, v22
	v_exp_f32_e32 v18, v23
	v_exp_f32_e32 v12, v12
	v_exp_f32_e32 v13, v13
	v_exp_f32_e32 v14, v14
	v_add_f32_e32 v0, 1.0, v0
	v_add_f32_e32 v15, 1.0, v15
	v_add_f32_e32 v16, 1.0, v16
	v_add_f32_e32 v17, 1.0, v17
	v_add_f32_e32 v18, 1.0, v18
	v_add_f32_e32 v19, 1.0, v12
	v_add_f32_e32 v20, 1.0, v13
	v_add_f32_e32 v21, 1.0, v14
	v_rcp_f32_e32 v12, v0
	v_rcp_f32_e32 v13, v15
	v_rcp_f32_e32 v14, v16
	v_rcp_f32_e32 v15, v17
	v_rcp_f32_e32 v16, v18
	v_rcp_f32_e32 v17, v19
	v_rcp_f32_e32 v18, v20
	v_rcp_f32_e32 v19, v21
	v_pk_mul_f32 v[2:3], v[2:3], v[12:13]
	v_pk_mul_f32 v[8:9], v[8:9], v[14:15]
	v_pk_mul_f32 v[12:13], v[6:7], v[16:17]
	v_pk_mul_f32 v[10:11], v[10:11], v[18:19]
	v_cvt_pk_bf16_f32 v6, v2, v3
	v_cvt_pk_bf16_f32 v7, v8, v9
	v_cvt_pk_bf16_f32 v8, v12, v13
	v_cvt_pk_bf16_f32 v9, v10, v11
	s_nop 0
	v_permlane32_swap_b32_e32 v6, v8
	v_permlane32_swap_b32_e32 v7, v9
	global_store_dwordx4 v[4:5], v[6:9], off offset:224
	s_cmpk_gt_i32 s33, 0x3ff
	s_cbranch_scc1 .LBB0_407

; template <bool DIFF>
; DI void attn_phase(const AttnArgs& a, char* lds) {
;     ...
;     f32x16 o[NM];
; #pragma unroll
;     for (int m = 0; m < NM; ++m)
; #pragma unroll
;       for (int r = 0; r < 16; ++r) o[m][r] = 0.f;
;     const float sbound = a.lamtab_all[DIFF ? 4 : 3];
;     const int usefix_i = __builtin_amdgcn_readfirstlane(sbound < 40.0f ? 1 : 0);
;     const bool usefix = usefix_i != 0;
;     float m_ref = usefix ? 0.f : -1e30f, l_sum = 0.f;
;     f32x16 negm;
; #pragma unroll
;     for (int r = 0; r < 16; ++r) negm[r] = 0.f;
;     if (t_beg < t_end) {
;       const int t2 = tid_pinned();
;       char* pb = lds + (t_beg & 1) * STAGE;
;       const u32 kofs = KOFS(t2) + (u32)t_beg * 64u * (u32)a.ldk, vofs = VOFS(t2) + (u32)t_beg * (u32)(DV * 64);
; #pragma unroll
;       for (int i = 0; i < NKR; ++i) GLDS16(a.K + kofs + i * 64, pb + wave * 1024 + 8192 * i);
; #pragma unroll
;       for (int i = 0; i < NVR; ++i) GLDS16(a.VT + vofs + i * 4096, pb + KBYTES + wave * 1024 + 8192 * i);
;       if (wave == 0) { const int l4 = t_beg * 64 + (t2 & 63); GLDS4(a.pos + l4, pb + KBYTES + VBYTES); GLDS4(a.posf + l4, pb + KBYTES + VBYTES + 256); }
;     }
;     __syncthreads();
; #pragma unroll 1
;     for (int t = t_beg; t < t_end; ++t) {
;       const char* sb = lds + (t & 1) * STAGE;
;       char* nb = lds + ((t + 1) & 1) * STAGE;
;       const bool nxt = t + 1 < t_end;
;       const int4 tinfo = *(const int4*)(ttab + 4 * t);
;       const int kcmin = __builtin_amdgcn_readfirstlane(tinfo.x), kcmax = __builtin_amdgcn_readfirstlane(tinfo.y);
;       bool skip = kcmin > wqcmax;
;       if (DIFF) {
;         const int tpmin = __builtin_amdgcn_readfirstlane(tinfo.z), tpmax = __builtin_amdgcn_readfirstlane(tinfo.w);
;         const int dist = max(0, max(wpmin - tpmax, tpmin - wpmax));
;         skip = skip || (slope2 * (float)dist > lim2);
;       }
;       const bool needmask = kcmax > wqcmin;
;     ...
;       if (!DIFF && uft != 0 && !skip) {
;         const int* pki = (const int*)(sb + KBYTES + VBYTES);
;         const int l2 = tid_pinned() & 63, l31b = l2 & 31, g2 = l2 >> 5;
;         const int prow = (((l31b >> 4) & 1) << 4) | (((l31b >> 2) & 1) << 3) | (((l31b >> 3) & 1) << 2) | (l31b & 3);
;         const int kx = g2 ^ ((prow >> 1) & 7);
;         const int koffb = prow * 128;
;         const int vx = g2 ^ ((l31b >> 1) & 7);
;         const int voffb = KBYTES + l31b * 128;
.LBB0_374:
	s_andn2_b64 vcc, exec, s[74:75]
	s_waitcnt vmcnt(0) lgkmcnt(0)
	s_barrier
	s_cbranch_vccnz .LBB0_369
	v_cvt_f32_i32_e32 v0, v2
	s_lshl_b32 s7, s33, 17
	s_lshl_b32 s5, s5, 21
	s_and_b32 s7, s7, 0x1c00000
	v_cvt_i32_f32_e32 v0, v0
	v_mov_b32_e32 v14, v1
	v_mov_b32_e32 v15, v1
	s_add_i32 s5, s7, s5
	v_ashrrev_i32_e32 v215, 6, v0
	v_mov_b32_e32 v0, v1
	v_mov_b32_e32 v2, v1
	v_mov_b32_e32 v3, v1
	v_mov_b32_e32 v4, v1
	v_mov_b32_e32 v5, v1
	v_mov_b32_e32 v6, v1
	v_mov_b32_e32 v7, v1
	v_mov_b32_e32 v8, v1
	v_mov_b32_e32 v9, v1
	v_mov_b32_e32 v10, v1
	v_mov_b32_e32 v11, v1
	v_mov_b32_e32 v12, v1
	v_mov_b32_e32 v13, v1
	v_mov_b64_e32 v[30:31], v[14:15]
	v_mov_b64_e32 v[46:47], v[14:15]
	v_mov_b64_e32 v[62:63], v[14:15]
	v_mov_b64_e32 v[78:79], v[14:15]
	v_cndmask_b32_e64 v214, 0, 1, s[10:11]
	s_mov_b32 s22, 0
	v_cndmask_b32_e64 v216, v211, 0, s[10:11]
	s_bitset1_b32 s5, 13
	v_mov_b32_e32 v217, 0
	s_mov_b32 s7, 0x20ff4
	s_mov_b32 s52, 64
	v_mov_b64_e32 v[28:29], v[12:13]
	v_mov_b64_e32 v[26:27], v[10:11]
	v_mov_b64_e32 v[24:25], v[8:9]
	v_mov_b64_e32 v[22:23], v[6:7]
	v_mov_b64_e32 v[20:21], v[4:5]
	v_mov_b64_e32 v[18:19], v[2:3]
	v_mov_b64_e32 v[16:17], v[0:1]
	v_mov_b64_e32 v[44:45], v[12:13]
	v_mov_b64_e32 v[42:43], v[10:11]
	v_mov_b64_e32 v[40:41], v[8:9]
	v_mov_b64_e32 v[38:39], v[6:7]
	v_mov_b64_e32 v[36:37], v[4:5]
	v_mov_b64_e32 v[34:35], v[2:3]
	v_mov_b64_e32 v[32:33], v[0:1]
	v_mov_b64_e32 v[60:61], v[12:13]
	v_mov_b64_e32 v[58:59], v[10:11]
	v_mov_b64_e32 v[56:57], v[8:9]
	v_mov_b64_e32 v[54:55], v[6:7]
	v_mov_b64_e32 v[52:53], v[4:5]
	v_mov_b64_e32 v[50:51], v[2:3]
	v_mov_b64_e32 v[48:49], v[0:1]
	v_mov_b64_e32 v[76:77], v[12:13]
	v_mov_b64_e32 v[74:75], v[10:11]
	v_mov_b64_e32 v[72:73], v[8:9]
	v_mov_b64_e32 v[70:71], v[6:7]
	v_mov_b64_e32 v[68:69], v[4:5]
	v_mov_b64_e32 v[66:67], v[2:3]
	v_mov_b64_e32 v[64:65], v[0:1]
	s_cmp_lt_u32 s59, 0x1000
	s_cbranch_scc1 .Lmla_noprio
	s_setprio 1
.Lmla_noprio:
.LBB0_376:
	s_add_i32 s10, s7, -4
	v_mov_b32_e32 v0, s10
	ds_read_b64 v[2:3], v0
	s_add_i32 s53, s22, 1
	s_bitcmp1_b32 s53, 0
	s_cselect_b32 s85, 0xa200, 0
	s_add_i32 s88, s85, s59
	s_waitcnt lgkmcnt(0)
	v_readfirstlane_b32 s11, v2
	v_readfirstlane_b32 s10, v3
	s_bitcmp1_b32 s22, 0
	v_mov_b32_e32 v0, v214
	s_cselect_b32 s63, 0xa200, 0
	s_cmp_gt_i32 s11, s1
	s_nop 0
	s_cselect_b64 s[74:75], -1, 0
	v_readfirstlane_b32 s22, v0
	s_cmp_eq_u32 s22, 0
	s_cselect_b64 s[86:87], -1, 0
	v_cmp_gt_i32_e64 s[10:11], s10, v213
	s_or_b64 s[86:87], s[86:87], s[74:75]
	s_and_b64 vcc, exec, s[86:87]
	v_cndmask_b32_e64 v0, 0, 1, s[10:11]
	v_cmp_ne_u32_e64 s[10:11], 1, v0
	s_cbranch_vccnz .Lmla_slow
	v_mov_b32_e32 v0, v208
	s_nop 0
	v_lshlrev_b32_e32 v2, 1, v0
	v_lshrrev_b32_e32 v3, 1, v0
	v_and_b32_e32 v2, 8, v2
	v_and_b32_e32 v3, 4, v3
	v_and_b32_e32 v4, 19, v0
	v_or3_b32 v2, v2, v4, v3
	v_bfe_u32 v15, v0, 5, 1
	v_lshrrev_b32_e32 v3, 1, v2
	v_bitop3_b32 v3, v3, v15, 7 bitop3:0x6c
	v_lshl_add_u32 v2, v2, 7, s63
	v_lshlrev_b32_e32 v3, 4, v3
	v_add_u32_e32 v172, v2, v3
	v_xad_u32 v176, v3, 32, v2
	v_xad_u32 v180, v3, 64, v2
	v_xad_u32 v226, v3, s82, v2
	ds_read_b128 v[2:5], v172
	ds_read_b128 v[84:87], v176
	ds_read_b128 v[10:13], v180
	ds_read_b128 v[164:167], v226
	ds_read_b128 v[6:9], v172 offset:8192
	ds_read_b128 v[92:95], v176 offset:8192
	ds_read_b128 v[80:83], v180 offset:8192
	ds_read_b128 v[168:171], v226 offset:8192
	ds_read_b128 v[88:91], v172 offset:16384
	ds_read_b128 v[160:163], v176 offset:16384
	ds_read_b128 v[218:221], v180 offset:16384
	ds_read_b128 v[222:225], v226 offset:16384
	v_lshrrev_b32_e32 v14, 5, v0
	v_bfe_u32 v96, v0, 1, 3
	v_lshlrev_b32_e32 v0, 7, v0
	v_and_b32_e32 v0, 0xf80, v0
	v_bitop3_b32 v14, v14, v96, 1 bitop3:0x6c
	v_lshrrev_b32_e32 v228, 4, v208
	v_xor_b32_e32 v228, v228, v208
	v_ashrrev_i32_e32 v230, 3, v208
	v_lshlrev_b32_e32 v228, 3, v228
	v_and_b32_e32 v231, 56, v228
	v_add_u32_e32 v228, s52, v230
	v_mul_lo_u32 v228, v228, s76
	v_mov_b32_e32 v229, 0
	v_add_u32_e32 v228, s4, v228
	v_or_b32_e32 v228, v228, v231
	v_lshl_add_u64 v[232:233], v[228:229], 1, s[14:15]
	v_lshl_or_b32 v228, v230, 6, v231
	v_add_u32_e32 v228, s5, v228
	v_lshl_add_u64 v[234:235], v[232:233], 0, s[16:17]
	v_lshl_add_u64 v[236:237], v[232:233], 0, s[18:19]
	v_lshl_add_u64 v[238:239], v[228:229], 1, s[40:41]
	v_lshl_add_u64 v[240:241], v[238:239], 0, s[68:69]
	v_and_b32_e32 v242, 63, v208
	v_add_u32_e32 v242, s52, v242
	v_ashrrev_i32_e32 v243, 31, v242
	v_lshlrev_b64 v[242:243], 2, v[242:243]
	v_lshl_add_u64 v[244:245], s[48:49], 0, v[242:243]
	v_lshl_add_u64 v[242:243], s[38:39], 0, v[242:243]
	s_add_i32 s89, s88, 0x2000
	s_add_i32 s90, s88, 0x4000
	s_add_i32 s91, s88, 0x6000
	s_add_i32 s32, s88, 0x8000
	s_cmp_ge_i32 s53, s0
	s_cselect_b64 vcc, -1, 0
	s_mov_b32 m0, s88
	s_waitcnt lgkmcnt(11)
	v_mfma_f32_32x32x16_bf16 v[96:111], v[2:5], v[112:115], 0
	s_cbranch_vccnz .Lmla_nd1
	global_load_lds_dwordx4 v[232:233], off
